# P12 fused final-norm tail: the 8 rowsq loads hoisted behind the panel-counter barrier, one wait, the 32 output stores per lane back to back (no per-row-group vmcnt(0) behind the write-through stores)
# speedup vs baseline: 1.0019x; 1.0019x over previous
;     __device__ __forceinline__ void fused(f32x4 (&acc)[2][2][4][2], const Unit& u, int wr, int wc, int fr, int fq, PG8_LAS unsigned char* lds, int wid, int lane) const {
;     ...
;         const __amdgpu_buffer_rsrc_t orsrc = __builtin_amdgcn_make_buffer_rsrc((void*)outf, (short)0, 16384 * 1024 * 4, 0x00020000);
;         f32x4 nwv[2][2];
; #pragma unroll
;         for (int bj = 0; bj < 2; ++bj)
; #pragma unroll
;             for (int n = 0; n < 2; ++n) nwv[bj][n] = *(const f32x4*)(nw + col0 + bj * HALF + n * 16);
; #pragma unroll
;         for (int ai = 0; ai < 2; ++ai)
; #pragma unroll
;             for (int m = 0; m < 4; ++m) { const int row = u.pm * BM + ai * HALF + wr * 64 + m * 16 + fr; const size_t off = (size_t)row * ldc + col0;
;                 const float rs = rsqrtf(__hip_atomic_load(rowsq + row, __ATOMIC_RELAXED, __HIP_MEMORY_SCOPE_AGENT) * (1.0f / 1024.0f) + 1e-6f);
; #pragma unroll
;                 for (int bj = 0; bj < 2; ++bj)
; #pragma unroll
;                     for (int n = 0; n < 2; ++n) { const f32x4 y = acc[ai][bj][m][n] * rs * nwv[bj][n]; __builtin_amdgcn_raw_buffer_store_b128(__builtin_bit_cast(u32x4, y), orsrc, (unsigned)((off + bj * HALF + n * 16) * 4), 0, 16); } }
.LBB0_1059:
	s_or_b64 exec, exec, s[0:1]
	v_lshl_add_u64 v[0:1], v[128:129], 2, s[56:57]
	s_barrier
	global_load_dword v244, v[134:135], off sc1
	global_load_dword v245, v[138:139], off sc1
	global_load_dword v246, v[142:143], off sc1
	global_load_dword v247, v[146:147], off sc1
	global_load_dword v248, v[150:151], off sc1
	global_load_dword v249, v[154:155], off sc1
	global_load_dword v250, v[164:165], off sc1
	global_load_dword v251, v[176:177], off sc1
	global_load_dwordx4 v[12:15], v[0:1], off
	global_load_dwordx4 v[8:11], v[0:1], off offset:64
	global_load_dwordx4 v[4:7], v[0:1], off offset:512
	s_nop 0
	global_load_dwordx4 v[0:3], v[0:1], off offset:576
	s_nop 0
	v_mov_b32_e32 v180, 0x358637bd
	s_mov_b32 s6, 0x800000
	v_lshlrev_b32_e32 v181, 2, v128
	s_and_b32 s1, s59, 0xffff
	s_mov_b32 s3, 0x20000
	s_brev_b32 s2, 32
	s_mov_b32 s0, s58
	s_waitcnt vmcnt(0)
	v_fmamk_f32 v25, v244, 0x3a800000, v180
	v_mul_f32_e32 v41, 0x4b800000, v25
	v_cmp_gt_f32_e32 vcc, s6, v25
	s_nop 1
	v_cndmask_b32_e32 v25, v25, v41, vcc
	v_rsq_f32_e32 v25, v25
	v_lshl_add_u32 v41, v130, 12, v181
	v_mul_f32_e32 v57, 0x45800000, v25
	v_cndmask_b32_e32 v128, v25, v57, vcc
	v_pk_mul_f32 v[130:131], v[132:133], v[128:129] op_sel_hi:[1,0]
	v_pk_mul_f32 v[126:127], v[126:127], v[128:129] op_sel_hi:[1,0]
	v_pk_mul_f32 v[124:125], v[124:125], v[128:129] op_sel_hi:[1,0]
	v_pk_mul_f32 v[122:123], v[122:123], v[128:129] op_sel_hi:[1,0]
	v_pk_mul_f32 v[132:133], v[116:117], v[128:129] op_sel_hi:[1,0]
	v_pk_mul_f32 v[134:135], v[118:119], v[128:129] op_sel_hi:[1,0]
	v_pk_mul_f32 v[178:179], v[112:113], v[128:129] op_sel_hi:[1,0]
	v_pk_mul_f32 v[128:129], v[114:115], v[128:129] op_sel_hi:[1,0]
	v_pk_mul_f32 v[114:115], v[14:15], v[126:127]
	v_pk_mul_f32 v[112:113], v[12:13], v[130:131]
	v_pk_mul_f32 v[118:119], v[10:11], v[122:123]
	v_pk_mul_f32 v[116:117], v[8:9], v[124:125]
	v_pk_mul_f32 v[124:125], v[6:7], v[134:135]
	v_pk_mul_f32 v[122:123], v[4:5], v[132:133]
	v_pk_mul_f32 v[128:129], v[2:3], v[128:129]
	v_pk_mul_f32 v[126:127], v[0:1], v[178:179]
	buffer_store_dwordx4 v[112:115], v41, s[0:3], 0 offen sc1
	buffer_store_dwordx4 v[116:119], v41, s[0:3], 0 offen offset:64 sc1
	buffer_store_dwordx4 v[122:125], v41, s[0:3], 0 offen offset:512 sc1
	buffer_store_dwordx4 v[126:129], v41, s[0:3], 0 offen offset:576 sc1
	v_fmamk_f32 v25, v245, 0x3a800000, v180
	v_mul_f32_e32 v41, 0x4b800000, v25
	v_cmp_gt_f32_e32 vcc, s6, v25
	s_nop 1
	v_cndmask_b32_e32 v25, v25, v41, vcc
	v_rsq_f32_e32 v25, v25
	v_lshl_add_u32 v41, v120, 12, v181
	v_mul_f32_e32 v57, 0x45800000, v25
	v_cndmask_b32_e32 v112, v25, v57, vcc
	v_pk_mul_f32 v[114:115], v[136:137], v[112:113] op_sel_hi:[1,0]
	v_pk_mul_f32 v[110:111], v[110:111], v[112:113] op_sel_hi:[1,0]
	v_pk_mul_f32 v[108:109], v[108:109], v[112:113] op_sel_hi:[1,0]
	v_pk_mul_f32 v[106:107], v[106:107], v[112:113] op_sel_hi:[1,0]
	v_pk_mul_f32 v[116:117], v[100:101], v[112:113] op_sel_hi:[1,0]
	v_pk_mul_f32 v[118:119], v[102:103], v[112:113] op_sel_hi:[1,0]
	v_pk_mul_f32 v[120:121], v[96:97], v[112:113] op_sel_hi:[1,0]
	v_pk_mul_f32 v[112:113], v[98:99], v[112:113] op_sel_hi:[1,0]
	v_pk_mul_f32 v[98:99], v[14:15], v[110:111]
	v_pk_mul_f32 v[96:97], v[12:13], v[114:115]
	v_pk_mul_f32 v[102:103], v[10:11], v[106:107]
	v_pk_mul_f32 v[100:101], v[8:9], v[108:109]
	v_pk_mul_f32 v[108:109], v[6:7], v[118:119]
	v_pk_mul_f32 v[106:107], v[4:5], v[116:117]
	v_pk_mul_f32 v[112:113], v[2:3], v[112:113]
	v_pk_mul_f32 v[110:111], v[0:1], v[120:121]
	buffer_store_dwordx4 v[96:99], v41, s[0:3], 0 offen sc1
	buffer_store_dwordx4 v[100:103], v41, s[0:3], 0 offen offset:64 sc1
	buffer_store_dwordx4 v[106:109], v41, s[0:3], 0 offen offset:512 sc1
	buffer_store_dwordx4 v[110:113], v41, s[0:3], 0 offen offset:576 sc1
	v_fmamk_f32 v25, v246, 0x3a800000, v180
	v_mul_f32_e32 v41, 0x4b800000, v25
	v_cmp_gt_f32_e32 vcc, s6, v25
	s_nop 1
	v_cndmask_b32_e32 v25, v25, v41, vcc
	v_rsq_f32_e32 v25, v25
	v_lshl_add_u32 v41, v104, 12, v181
	v_mul_f32_e32 v57, 0x45800000, v25
	v_cndmask_b32_e32 v96, v25, v57, vcc
	v_pk_mul_f32 v[98:99], v[140:141], v[96:97] op_sel_hi:[1,0]
	v_pk_mul_f32 v[94:95], v[94:95], v[96:97] op_sel_hi:[1,0]
	v_pk_mul_f32 v[92:93], v[92:93], v[96:97] op_sel_hi:[1,0]
	v_pk_mul_f32 v[90:91], v[90:91], v[96:97] op_sel_hi:[1,0]
	v_pk_mul_f32 v[100:101], v[84:85], v[96:97] op_sel_hi:[1,0]
	v_pk_mul_f32 v[102:103], v[86:87], v[96:97] op_sel_hi:[1,0]
	v_pk_mul_f32 v[104:105], v[80:81], v[96:97] op_sel_hi:[1,0]
	v_pk_mul_f32 v[96:97], v[82:83], v[96:97] op_sel_hi:[1,0]
	v_pk_mul_f32 v[82:83], v[14:15], v[94:95]
	v_pk_mul_f32 v[80:81], v[12:13], v[98:99]
	v_pk_mul_f32 v[86:87], v[10:11], v[90:91]
	v_pk_mul_f32 v[84:85], v[8:9], v[92:93]
	v_pk_mul_f32 v[92:93], v[6:7], v[102:103]
	v_pk_mul_f32 v[90:91], v[4:5], v[100:101]
	v_pk_mul_f32 v[96:97], v[2:3], v[96:97]
	v_pk_mul_f32 v[94:95], v[0:1], v[104:105]
	buffer_store_dwordx4 v[80:83], v41, s[0:3], 0 offen sc1
	buffer_store_dwordx4 v[84:87], v41, s[0:3], 0 offen offset:64 sc1
	buffer_store_dwordx4 v[90:93], v41, s[0:3], 0 offen offset:512 sc1
	buffer_store_dwordx4 v[94:97], v41, s[0:3], 0 offen offset:576 sc1
	v_fmamk_f32 v25, v247, 0x3a800000, v180
	v_mul_f32_e32 v41, 0x4b800000, v25
	v_cmp_gt_f32_e32 vcc, s6, v25
	s_nop 1
	v_cndmask_b32_e32 v25, v25, v41, vcc
	v_rsq_f32_e32 v25, v25
	v_lshl_add_u32 v41, v88, 12, v181
	v_mul_f32_e32 v57, 0x45800000, v25
	v_cndmask_b32_e32 v80, v25, v57, vcc
	v_pk_mul_f32 v[82:83], v[144:145], v[80:81] op_sel_hi:[1,0]
	v_pk_mul_f32 v[78:79], v[78:79], v[80:81] op_sel_hi:[1,0]
	v_pk_mul_f32 v[76:77], v[76:77], v[80:81] op_sel_hi:[1,0]
	v_pk_mul_f32 v[74:75], v[74:75], v[80:81] op_sel_hi:[1,0]
;     __device__ __forceinline__ void fused(f32x4 (&acc)[2][2][4][2], const Unit& u, int wr, int wc, int fr, int fq, PG8_LAS unsigned char* lds, int wid, int lane) const {
;     ...
;             for (int m = 0; m < 4; ++m) { const int row = u.pm * BM + ai * HALF + wr * 64 + m * 16 + fr; const size_t off = (size_t)row * ldc + col0;
;                 const float rs = rsqrtf(__hip_atomic_load(rowsq + row, __ATOMIC_RELAXED, __HIP_MEMORY_SCOPE_AGENT) * (1.0f / 1024.0f) + 1e-6f);
; #pragma unroll
;                 for (int bj = 0; bj < 2; ++bj)
; #pragma unroll
;                     for (int n = 0; n < 2; ++n) { const f32x4 y = acc[ai][bj][m][n] * rs * nwv[bj][n]; __builtin_amdgcn_raw_buffer_store_b128(__builtin_bit_cast(u32x4, y), orsrc, (unsigned)((off + bj * HALF + n * 16) * 4), 0, 16); } }
	v_pk_mul_f32 v[84:85], v[68:69], v[80:81] op_sel_hi:[1,0]
	v_pk_mul_f32 v[86:87], v[70:71], v[80:81] op_sel_hi:[1,0]
	v_pk_mul_f32 v[88:89], v[64:65], v[80:81] op_sel_hi:[1,0]
	v_pk_mul_f32 v[80:81], v[66:67], v[80:81] op_sel_hi:[1,0]
	v_pk_mul_f32 v[66:67], v[14:15], v[78:79]
	v_pk_mul_f32 v[64:65], v[12:13], v[82:83]
	v_pk_mul_f32 v[70:71], v[10:11], v[74:75]
	v_pk_mul_f32 v[68:69], v[8:9], v[76:77]
	v_pk_mul_f32 v[76:77], v[6:7], v[86:87]
	v_pk_mul_f32 v[74:75], v[4:5], v[84:85]
	v_pk_mul_f32 v[80:81], v[2:3], v[80:81]
	v_pk_mul_f32 v[78:79], v[0:1], v[88:89]
	buffer_store_dwordx4 v[64:67], v41, s[0:3], 0 offen sc1
	buffer_store_dwordx4 v[68:71], v41, s[0:3], 0 offen offset:64 sc1
	buffer_store_dwordx4 v[74:77], v41, s[0:3], 0 offen offset:512 sc1
	buffer_store_dwordx4 v[78:81], v41, s[0:3], 0 offen offset:576 sc1
	v_fmamk_f32 v25, v248, 0x3a800000, v180
	v_mul_f32_e32 v41, 0x4b800000, v25
	v_cmp_gt_f32_e32 vcc, s6, v25
	s_nop 1
	v_cndmask_b32_e32 v25, v25, v41, vcc
	v_rsq_f32_e32 v25, v25
	v_lshl_add_u32 v41, v72, 12, v181
	v_mul_f32_e32 v57, 0x45800000, v25
	v_cndmask_b32_e32 v64, v25, v57, vcc
	v_pk_mul_f32 v[66:67], v[148:149], v[64:65] op_sel_hi:[1,0]
	v_pk_mul_f32 v[62:63], v[62:63], v[64:65] op_sel_hi:[1,0]
	v_pk_mul_f32 v[60:61], v[60:61], v[64:65] op_sel_hi:[1,0]
	v_pk_mul_f32 v[58:59], v[58:59], v[64:65] op_sel_hi:[1,0]
	v_pk_mul_f32 v[68:69], v[52:53], v[64:65] op_sel_hi:[1,0]
	v_pk_mul_f32 v[70:71], v[54:55], v[64:65] op_sel_hi:[1,0]
	v_pk_mul_f32 v[72:73], v[48:49], v[64:65] op_sel_hi:[1,0]
	v_pk_mul_f32 v[64:65], v[50:51], v[64:65] op_sel_hi:[1,0]
	v_pk_mul_f32 v[50:51], v[14:15], v[62:63]
	v_pk_mul_f32 v[48:49], v[12:13], v[66:67]
	v_pk_mul_f32 v[54:55], v[10:11], v[58:59]
	v_pk_mul_f32 v[52:53], v[8:9], v[60:61]
	v_pk_mul_f32 v[60:61], v[6:7], v[70:71]
	v_pk_mul_f32 v[58:59], v[4:5], v[68:69]
	v_pk_mul_f32 v[64:65], v[2:3], v[64:65]
	v_pk_mul_f32 v[62:63], v[0:1], v[72:73]
	buffer_store_dwordx4 v[48:51], v41, s[0:3], 0 offen sc1
	buffer_store_dwordx4 v[52:55], v41, s[0:3], 0 offen offset:64 sc1
	buffer_store_dwordx4 v[58:61], v41, s[0:3], 0 offen offset:512 sc1
	buffer_store_dwordx4 v[62:65], v41, s[0:3], 0 offen offset:576 sc1
	v_fmamk_f32 v25, v249, 0x3a800000, v180
	v_mul_f32_e32 v41, 0x4b800000, v25
	v_cmp_gt_f32_e32 vcc, s6, v25
	s_nop 1
	v_cndmask_b32_e32 v25, v25, v41, vcc
	v_rsq_f32_e32 v25, v25
	v_lshl_add_u32 v41, v56, 12, v181
	v_mul_f32_e32 v48, 0x45800000, v25
	v_cndmask_b32_e32 v48, v25, v48, vcc
	v_pk_mul_f32 v[50:51], v[152:153], v[48:49] op_sel_hi:[1,0]
	v_pk_mul_f32 v[46:47], v[46:47], v[48:49] op_sel_hi:[1,0]
	v_pk_mul_f32 v[44:45], v[44:45], v[48:49] op_sel_hi:[1,0]
	v_pk_mul_f32 v[42:43], v[42:43], v[48:49] op_sel_hi:[1,0]
	v_pk_mul_f32 v[52:53], v[36:37], v[48:49] op_sel_hi:[1,0]
	v_pk_mul_f32 v[54:55], v[38:39], v[48:49] op_sel_hi:[1,0]
	v_pk_mul_f32 v[56:57], v[32:33], v[48:49] op_sel_hi:[1,0]
	v_pk_mul_f32 v[48:49], v[34:35], v[48:49] op_sel_hi:[1,0]
	v_pk_mul_f32 v[34:35], v[14:15], v[46:47]
	v_pk_mul_f32 v[32:33], v[12:13], v[50:51]
	v_pk_mul_f32 v[38:39], v[10:11], v[42:43]
	v_pk_mul_f32 v[36:37], v[8:9], v[44:45]
	v_pk_mul_f32 v[44:45], v[6:7], v[54:55]
	v_pk_mul_f32 v[42:43], v[4:5], v[52:53]
	v_pk_mul_f32 v[48:49], v[2:3], v[48:49]
	v_pk_mul_f32 v[46:47], v[0:1], v[56:57]
	buffer_store_dwordx4 v[32:35], v41, s[0:3], 0 offen sc1
	buffer_store_dwordx4 v[36:39], v41, s[0:3], 0 offen offset:64 sc1
	buffer_store_dwordx4 v[42:45], v41, s[0:3], 0 offen offset:512 sc1
	buffer_store_dwordx4 v[46:49], v41, s[0:3], 0 offen offset:576 sc1
	v_lshl_add_u32 v42, v40, 12, v181
	v_fmamk_f32 v25, v250, 0x3a800000, v180
	v_mul_f32_e32 v32, 0x4b800000, v25
	v_cmp_gt_f32_e32 vcc, s6, v25
	s_nop 1
	v_cndmask_b32_e32 v25, v25, v32, vcc
	v_rsq_f32_e32 v25, v25
	s_nop 0
	v_mul_f32_e32 v32, 0x45800000, v25
	v_cndmask_b32_e32 v32, v25, v32, vcc
	v_pk_mul_f32 v[34:35], v[156:157], v[32:33] op_sel_hi:[1,0]
	v_pk_mul_f32 v[30:31], v[30:31], v[32:33] op_sel_hi:[1,0]
	v_pk_mul_f32 v[28:29], v[28:29], v[32:33] op_sel_hi:[1,0]
	v_pk_mul_f32 v[26:27], v[26:27], v[32:33] op_sel_hi:[1,0]
	v_pk_mul_f32 v[36:37], v[20:21], v[32:33] op_sel_hi:[1,0]
	v_pk_mul_f32 v[38:39], v[22:23], v[32:33] op_sel_hi:[1,0]
	v_pk_mul_f32 v[40:41], v[16:17], v[32:33] op_sel_hi:[1,0]
	v_pk_mul_f32 v[32:33], v[18:19], v[32:33] op_sel_hi:[1,0]
	v_pk_mul_f32 v[18:19], v[14:15], v[30:31]
	v_pk_mul_f32 v[16:17], v[12:13], v[34:35]
	v_pk_mul_f32 v[22:23], v[10:11], v[26:27]
	v_pk_mul_f32 v[20:21], v[8:9], v[28:29]
	v_pk_mul_f32 v[28:29], v[6:7], v[38:39]
	v_pk_mul_f32 v[26:27], v[4:5], v[36:37]
	v_pk_mul_f32 v[32:33], v[2:3], v[32:33]
	v_pk_mul_f32 v[30:31], v[0:1], v[40:41]
	buffer_store_dwordx4 v[16:19], v42, s[0:3], 0 offen sc1
	buffer_store_dwordx4 v[20:23], v42, s[0:3], 0 offen offset:64 sc1
	buffer_store_dwordx4 v[26:29], v42, s[0:3], 0 offen offset:512 sc1
	buffer_store_dwordx4 v[30:33], v42, s[0:3], 0 offen offset:576 sc1
	v_fmac_f32_e32 v180, 0x3a800000, v251
	v_mul_f32_e32 v16, 0x4b800000, v180
	v_cmp_gt_f32_e32 vcc, s6, v180
	v_lshl_add_u32 v32, v24, 12, v181
	s_nop 0
	v_cndmask_b32_e32 v16, v180, v16, vcc
	v_rsq_f32_e32 v16, v16
	s_nop 0
	v_mul_f32_e32 v17, 0x45800000, v16
	v_cndmask_b32_e32 v16, v16, v17, vcc
	v_pk_mul_f32 v[18:19], v[174:175], v[16:17] op_sel_hi:[1,0]
	v_pk_mul_f32 v[20:21], v[172:173], v[16:17] op_sel_hi:[1,0]
	v_pk_mul_f32 v[22:23], v[170:171], v[16:17] op_sel_hi:[1,0]
	v_pk_mul_f32 v[24:25], v[168:169], v[16:17] op_sel_hi:[1,0]
	v_pk_mul_f32 v[26:27], v[166:167], v[16:17] op_sel_hi:[1,0]
	v_pk_mul_f32 v[28:29], v[160:161], v[16:17] op_sel_hi:[1,0]
	v_pk_mul_f32 v[30:31], v[162:163], v[16:17] op_sel_hi:[1,0]
	v_pk_mul_f32 v[16:17], v[158:159], v[16:17] op_sel_hi:[1,0]
	v_pk_mul_f32 v[14:15], v[14:15], v[20:21]
	v_pk_mul_f32 v[12:13], v[12:13], v[18:19]
	v_pk_mul_f32 v[10:11], v[10:11], v[24:25]
	v_pk_mul_f32 v[8:9], v[8:9], v[22:23]
	v_pk_mul_f32 v[6:7], v[6:7], v[28:29]
	v_pk_mul_f32 v[4:5], v[4:5], v[26:27]
	v_pk_mul_f32 v[2:3], v[2:3], v[16:17]
	v_pk_mul_f32 v[0:1], v[0:1], v[30:31]
	buffer_store_dwordx4 v[12:15], v32, s[0:3], 0 offen sc1
	buffer_store_dwordx4 v[8:11], v32, s[0:3], 0 offen offset:64 sc1
	buffer_store_dwordx4 v[4:7], v32, s[0:3], 0 offen offset:512 sc1
	buffer_store_dwordx4 v[0:3], v32, s[0:3], 0 offen offset:576 sc1
